# grid barrier: the arrival-time invalidate is issued right after the arrival atomic instead of before it, so its latency overlaps the atomic round trip and no longer delays arrival
# speedup vs baseline: 1.0145x; 1.0006x over previous
.Lgs0_b173:
	s_or_b64 exec, exec, s[18:19]
	buffer_inv sc1
	v_cvt_f32_u32_e32 v4, v2
	s_waitcnt vmcnt(0)
	v_readfirstlane_b32 s18, v3
	v_sub_u32_e32 v3, 0, v2
	v_rcp_iflag_f32_e32 v4, v4
	v_add_u32_e32 v5, s18, v1
	v_mul_f32_e32 v4, 0x4f7ffffe, v4
	v_cvt_u32_f32_e32 v4, v4
	v_mul_lo_u32 v1, v3, v4
	v_mul_hi_u32 v1, v4, v1
	v_add_u32_e32 v1, v4, v1
	v_mul_hi_u32 v1, v5, v1
	v_mul_lo_u32 v3, v1, v2
	v_sub_u32_e32 v3, v5, v3
	v_add_u32_e32 v4, 1, v1
	v_cmp_ge_u32_e32 vcc, v3, v2
	s_nop 1
	v_cndmask_b32_e32 v1, v1, v4, vcc
	v_sub_u32_e32 v4, v3, v2
	v_cndmask_b32_e32 v3, v3, v4, vcc
	v_add_u32_e32 v4, 1, v1
	v_cmp_ge_u32_e32 vcc, v3, v2
	v_add_u32_e32 v3, 1, v5
	s_nop 0
	v_cndmask_b32_e32 v1, v1, v4, vcc
	v_mul_lo_u32 v4, v2, v1
	v_add_u32_e32 v2, v4, v2
	v_cmp_ne_u32_e32 vcc, v3, v2
	s_and_saveexec_b64 s[18:19], vcc
	s_xor_b64 s[18:19], exec, s[18:19]
	s_cbranch_execz .Lgs0_b187
	v_readlane_b32 s22, v255, 0
	v_readlane_b32 s23, v255, 1
	s_waitcnt lgkmcnt(0)
	s_nop 3
	global_load_dword v0, v17, s[22:23] sc1
	s_waitcnt vmcnt(0)
	v_cmp_eq_u32_e32 vcc, v0, v1
	s_and_saveexec_b64 s[22:23], vcc
	s_cbranch_execz .Lgs0_b186
	s_mov_b32 s24, 1
	s_mov_b64 s[28:29], 0
	s_branch .Lgs0_b177

.LBB0_604:
	s_or_b64 exec, exec, s[18:19]
	buffer_inv sc1
	v_cvt_f32_u32_e32 v4, v2
	s_waitcnt vmcnt(0)
	v_readfirstlane_b32 s18, v3
	v_sub_u32_e32 v3, 0, v2
	v_rcp_iflag_f32_e32 v4, v4
	v_add_u32_e32 v5, s18, v1
	v_mul_f32_e32 v4, 0x4f7ffffe, v4
	v_cvt_u32_f32_e32 v4, v4
	v_mul_lo_u32 v1, v3, v4
	v_mul_hi_u32 v1, v4, v1
	v_add_u32_e32 v1, v4, v1
	v_mul_hi_u32 v1, v5, v1
	v_mul_lo_u32 v3, v1, v2
	v_sub_u32_e32 v3, v5, v3
	v_add_u32_e32 v4, 1, v1
	v_cmp_ge_u32_e32 vcc, v3, v2
	s_nop 1
	v_cndmask_b32_e32 v1, v1, v4, vcc
	v_sub_u32_e32 v4, v3, v2
	v_cndmask_b32_e32 v3, v3, v4, vcc
	v_add_u32_e32 v4, 1, v1
	v_cmp_ge_u32_e32 vcc, v3, v2
	v_add_u32_e32 v3, 1, v5
	s_nop 0
	v_cndmask_b32_e32 v1, v1, v4, vcc
	v_mul_lo_u32 v4, v2, v1
	v_add_u32_e32 v2, v4, v2
	v_cmp_ne_u32_e32 vcc, v3, v2
	s_and_saveexec_b64 s[18:19], vcc
	s_xor_b64 s[18:19], exec, s[18:19]
	s_cbranch_execz .LBB0_618
	v_readlane_b32 s22, v255, 0
	v_readlane_b32 s23, v255, 1
	s_waitcnt lgkmcnt(0)
	s_nop 3
	global_load_dword v0, v17, s[22:23] sc1
	s_waitcnt vmcnt(0)
	v_cmp_eq_u32_e32 vcc, v0, v1
	s_and_saveexec_b64 s[22:23], vcc
	s_cbranch_execz .LBB0_617
	s_mov_b32 s24, 1
	s_mov_b64 s[26:27], 0
	s_branch .LBB0_608

.LBB0_674:
	s_or_b64 exec, exec, s[14:15]
	buffer_inv sc1
	v_cvt_f32_u32_e32 v4, v2
	s_waitcnt vmcnt(0)
	v_readfirstlane_b32 s14, v3
	v_sub_u32_e32 v3, 0, v2
	v_rcp_iflag_f32_e32 v4, v4
	v_add_u32_e32 v5, s14, v1
	v_mul_f32_e32 v4, 0x4f7ffffe, v4
	v_cvt_u32_f32_e32 v4, v4
	v_mul_lo_u32 v1, v3, v4
	v_mul_hi_u32 v1, v4, v1
	v_add_u32_e32 v1, v4, v1
	v_mul_hi_u32 v1, v5, v1
	v_mul_lo_u32 v3, v1, v2
	v_sub_u32_e32 v3, v5, v3
	v_add_u32_e32 v4, 1, v1
	v_cmp_ge_u32_e32 vcc, v3, v2
	s_nop 1
	v_cndmask_b32_e32 v1, v1, v4, vcc
	v_sub_u32_e32 v4, v3, v2
	v_cndmask_b32_e32 v3, v3, v4, vcc
	v_add_u32_e32 v4, 1, v1
	v_cmp_ge_u32_e32 vcc, v3, v2
	v_add_u32_e32 v3, 1, v5
	s_nop 0
	v_cndmask_b32_e32 v1, v1, v4, vcc
	v_mul_lo_u32 v4, v2, v1
	v_add_u32_e32 v2, v4, v2
	v_cmp_ne_u32_e32 vcc, v3, v2
	s_and_saveexec_b64 s[14:15], vcc
	s_xor_b64 s[14:15], exec, s[14:15]
	s_cbranch_execz .LBB0_688
	v_readlane_b32 s18, v255, 0
	v_readlane_b32 s19, v255, 1
	s_waitcnt lgkmcnt(0)
	s_nop 3
	global_load_dword v0, v17, s[18:19] sc1
	s_waitcnt vmcnt(0)
	v_cmp_eq_u32_e32 vcc, v0, v1
	s_and_saveexec_b64 s[18:19], vcc
	s_cbranch_execz .LBB0_687
	s_mov_b32 s36, 1
	s_mov_b64 s[22:23], 0
	s_branch .LBB0_678

.LBB0_742:
	s_or_b64 exec, exec, s[14:15]
	buffer_inv sc1
	v_cvt_f32_u32_e32 v4, v2
	s_waitcnt vmcnt(0)
	v_readfirstlane_b32 s14, v3
	v_sub_u32_e32 v3, 0, v2
	v_rcp_iflag_f32_e32 v4, v4
	v_add_u32_e32 v5, s14, v1
	v_mul_f32_e32 v4, 0x4f7ffffe, v4
	v_cvt_u32_f32_e32 v4, v4
	v_mul_lo_u32 v1, v3, v4
	v_mul_hi_u32 v1, v4, v1
	v_add_u32_e32 v1, v4, v1
	v_mul_hi_u32 v1, v5, v1
	v_mul_lo_u32 v3, v1, v2
	v_sub_u32_e32 v3, v5, v3
	v_add_u32_e32 v4, 1, v1
	v_cmp_ge_u32_e32 vcc, v3, v2
	s_nop 1
	v_cndmask_b32_e32 v1, v1, v4, vcc
	v_sub_u32_e32 v4, v3, v2
	v_cndmask_b32_e32 v3, v3, v4, vcc
	v_add_u32_e32 v4, 1, v1
	v_cmp_ge_u32_e32 vcc, v3, v2
	v_add_u32_e32 v3, 1, v5
	s_nop 0
	v_cndmask_b32_e32 v1, v1, v4, vcc
	v_mul_lo_u32 v4, v2, v1
	v_add_u32_e32 v2, v4, v2
	v_cmp_ne_u32_e32 vcc, v3, v2
	s_and_saveexec_b64 s[14:15], vcc
	s_xor_b64 s[14:15], exec, s[14:15]
	s_cbranch_execz .LBB0_756
	v_readlane_b32 s18, v255, 0
	v_readlane_b32 s19, v255, 1
	s_waitcnt lgkmcnt(0)
	s_nop 3
	global_load_dword v0, v17, s[18:19] sc1
	s_waitcnt vmcnt(0)
	v_cmp_eq_u32_e32 vcc, v0, v1
	s_and_saveexec_b64 s[18:19], vcc
	s_cbranch_execz .LBB0_755
	s_mov_b32 s24, 1
	s_mov_b64 s[22:23], 0
	s_branch .LBB0_746
